# rownorm row loop: lane mapping changed so every global load/store instruction covers a contiguous span (lane owns 4 columns per 256-column quarter)
# speedup vs baseline: 1.0173x; 1.0119x over previous
; __device__ __forceinline__ void rn_load(RowRegs& R, const float* base, const bf16_t* y, int lane) {
; #pragma unroll
;     for (int j = 0; j < 2; ++j) { R.v[2 * j] = __builtin_nontemporal_load((const f32x4*)(base + 512 * j + 8 * lane)); R.v[2 * j + 1] = __builtin_nontemporal_load((const f32x4*)(base + 512 * j + 8 * lane + 4)); if (y) R.y[j] = __builtin_nontemporal_load((const u32x4*)(y + 512 * j + 8 * lane)); }
; }
; __device__ __forceinline__ void phase_rownorm(ArgsK& a, int idx, int bid, int G, int tid, int wave, int lane, unsigned* cnt) {
;     const int layer = idx / 3, k = idx % 3; const float* ng = a.in[7] + (size_t)layer * 6 * DM;
;     const float* gpost = ng + (2 * k + 1) * DM; const float scale = (k == 1) ? 1.0f : 0.5f;
;     const float* gpre = (k < 2) ? ng + (2 * k + 2) * DM : (layer == 0 ? a.in[7] + 6 * DM : nullptr);
;     float* X = a.out; const bf16_t* Y = (const bf16_t*)(a.ws + WS_Y); bf16_t* HN = (bf16_t*)(a.ws + WS_HN);
;     if (bid < N_TAIL) return;
;     const int gw = (bid - N_TAIL) * 8 + wave, NGW = (G - N_TAIL) * 8;
;     for (int m = gw; m < MP; m += 2 * NGW) {
;         const int m2 = m + NGW; const bool two = m2 < MP;
;         const float* b0 = (idx == 0) ? a.in[0] + (size_t)m * DM : X + (size_t)m * DM;
;         const float* b1 = (idx == 0) ? a.in[0] + (size_t)m2 * DM : X + (size_t)m2 * DM;
;         RowRegs R0, R1; rn_load(R0, b0, Y + (size_t)m * DM, lane); if (two) rn_load(R1, b1, Y + (size_t)m2 * DM, lane);
;         rn_finish(R0, true, gpost, scale, X + (size_t)m * DM, gpre, gpre ? HN + (size_t)m * DM : nullptr, lane);
;         if (two) rn_finish(R1, true, gpost, scale, X + (size_t)m2 * DM, gpre, gpre ? HN + (size_t)m2 * DM : nullptr, lane); }
.LBB0_640:
	s_andn2_b64 vcc, exec, s[2:3]
	s_cbranch_vccnz .LBB0_679
	v_readlane_b32 s5, v254, 14
	s_add_i32 s4, s5, -3
	s_and_b64 s[2:3], s[44:45], exec
	s_load_dwordx2 s[2:3], s[38:39], 0x38
	s_load_dwordx2 s[16:17], s[38:39], 0xf0
	s_cselect_b32 s6, s5, s4
	v_readlane_b32 s4, v254, 15
	v_readlane_b32 s5, v254, 16
	s_lshl_b64 s[4:5], s[4:5], 2
	s_waitcnt lgkmcnt(0)
	s_add_u32 s7, s2, s4
	s_addc_u32 s8, s3, s5
	s_lshl_b32 s12, s6, 11
	s_lshl_b64 s[4:5], s[12:13], 2
	s_add_u32 s7, s7, s4
	s_addc_u32 s8, s8, s5
	s_add_u32 s10, s7, 0x1000
	s_addc_u32 s11, s8, 0
	s_cmp_eq_u32 s6, 1
	s_cselect_b64 s[4:5], -1, 0
	s_waitcnt vmcnt(0)
	v_cndmask_b32_e64 v69, 0.5, 1.0, s[4:5]
	s_add_u32 s4, s7, 0x2000
	s_addc_u32 s5, s8, 0
	s_add_u32 s7, s2, 0x6000
	s_addc_u32 s8, s3, 0
	s_and_b64 s[2:3], s[44:45], exec
	s_cselect_b32 s2, s7, 0
	s_cselect_b32 s3, s8, 0
	s_cmp_lt_u32 s6, 2
	s_cselect_b32 s3, s5, s3
	s_cselect_b32 s2, s4, s2
	s_add_u32 s8, s40, 0x6000000
	s_addc_u32 s9, s41, 0
	s_add_i32 s12, s77, -8
	s_lshl_b32 s4, s12, 3
	v_readlane_b32 s5, v254, 13
	s_add_i32 s24, s4, s5
	s_cmp_gt_i32 s24, 0xffff
	v_lshlrev_b32_e32 v50, 4, v158
	v_lshlrev_b32_e32 v0, 5, v158
	s_cbranch_scc1 .LBB0_655
	s_load_dwordx2 s[4:5], s[38:39], 0x0
	s_sub_i32 s44, s62, 64
	s_cmp_lg_u64 s[2:3], 0
	s_cselect_b64 s[40:41], -1, 0
	s_cmp_lg_u64 s[16:17], 0
	s_cselect_b64 s[42:43], -1, 0
	s_and_b64 s[6:7], s[46:47], exec
	v_mov_b32_e32 v51, v1
	s_waitcnt lgkmcnt(0)
	s_cselect_b32 s5, s5, s17
	s_cselect_b32 s4, s4, s16
	v_lshlrev_b32_e32 v2, 3, v158
	v_mov_b32_e32 v3, v1
	v_lshl_add_u64 v[52:53], s[0:1], 0, v[2:3]
	v_lshl_add_u64 v[54:55], s[10:11], 0, v[50:51]
	v_lshl_add_u64 v[56:57], s[16:17], 0, v[50:51]
	v_lshl_add_u64 v[58:59], s[2:3], 0, v[50:51]
	v_lshl_add_u64 v[60:61], s[8:9], 0, v[2:3]
	v_lshl_add_u64 v[62:63], s[4:5], 0, v[50:51]
	s_mov_b32 s19, 0
	s_mov_b32 s29, 0
	s_mov_b32 s35, 0
	s_mov_b32 s5, 0
	global_load_dwordx4 v[96:99], v[54:55], off offset:0
	global_load_dwordx4 v[100:103], v[54:55], off offset:1024
	global_load_dwordx4 v[104:107], v[54:55], off offset:2048
	global_load_dwordx4 v[108:111], v[54:55], off offset:3072
	s_andn2_b64 vcc, exec, s[40:41]
	s_cbranch_vccnz .Lrn_nogpre
	global_load_dwordx4 v[112:115], v[58:59], off offset:0
	global_load_dwordx4 v[116:119], v[58:59], off offset:1024
	global_load_dwordx4 v[120:123], v[58:59], off offset:2048
	global_load_dwordx4 v[124:127], v[58:59], off offset:3072
.Lrn_nogpre:
	s_mov_b32 s25, s24
	s_lshl_b32 s34, s25, 12
	s_lshl_b32 s4, s25, 11
	v_lshl_add_u64 v[228:229], v[62:63], 0, s[34:35]
	v_lshl_add_u64 v[230:231], v[52:53], 0, s[4:5]
	global_load_dwordx4 v[2:5], v[228:229], off nt
	global_load_dwordx4 v[6:9], v[228:229], off offset:1024 nt
	global_load_dwordx4 v[10:13], v[228:229], off offset:2048 nt
	global_load_dwordx4 v[14:17], v[228:229], off offset:3072 nt
	global_load_dwordx2 v[18:19], v[230:231], off nt
	global_load_dwordx2 v[20:21], v[230:231], off offset:512 nt
	global_load_dwordx2 v[22:23], v[230:231], off offset:1024 nt
	global_load_dwordx2 v[24:25], v[230:231], off offset:1536 nt
	s_add_i32 s25, s25, s44
	s_cmp_lt_i32 s25, 0x10000
	s_cselect_b32 s25, s25, s24
	s_lshl_b32 s34, s25, 12
	s_lshl_b32 s4, s25, 11
	v_lshl_add_u64 v[228:229], v[62:63], 0, s[34:35]
	v_lshl_add_u64 v[230:231], v[52:53], 0, s[4:5]
	global_load_dwordx4 v[26:29], v[228:229], off nt
	global_load_dwordx4 v[30:33], v[228:229], off offset:1024 nt
	global_load_dwordx4 v[34:37], v[228:229], off offset:2048 nt
	global_load_dwordx4 v[38:41], v[228:229], off offset:3072 nt
	global_load_dwordx2 v[42:43], v[230:231], off nt
	global_load_dwordx2 v[44:45], v[230:231], off offset:512 nt
	global_load_dwordx2 v[46:47], v[230:231], off offset:1024 nt
	global_load_dwordx2 v[48:49], v[230:231], off offset:1536 nt
	s_add_i32 s25, s25, s44
	s_cmp_lt_i32 s25, 0x10000
	s_cselect_b32 s25, s25, s24
	s_lshl_b32 s34, s25, 12
	s_lshl_b32 s4, s25, 11
	v_lshl_add_u64 v[228:229], v[62:63], 0, s[34:35]
	v_lshl_add_u64 v[230:231], v[52:53], 0, s[4:5]
	global_load_dwordx4 v[70:73], v[228:229], off nt
	global_load_dwordx4 v[74:77], v[228:229], off offset:1024 nt
	global_load_dwordx4 v[78:81], v[228:229], off offset:2048 nt
	global_load_dwordx4 v[82:85], v[228:229], off offset:3072 nt
	global_load_dwordx2 v[86:87], v[230:231], off nt
	global_load_dwordx2 v[88:89], v[230:231], off offset:512 nt
	global_load_dwordx2 v[90:91], v[230:231], off offset:1024 nt
	global_load_dwordx2 v[92:93], v[230:231], off offset:1536 nt
	s_waitcnt vmcnt(0)
; __device__ __forceinline__ unsigned cvt_pk_bf16(float lo, float hi) { unsigned r; asm volatile("v_cvt_pk_bf16_f32 %0, %1, %2" : "=v"(r) : "v"(lo), "v"(hi)); return r; }
; __device__ __forceinline__ float bf2f(unsigned short b) { return __uint_as_float(((unsigned)b) << 16); }
; __device__ __forceinline__ void rn_finish(RowRegs& R, bool hasy, const float* gpost, float scale, float* xo, const float* gpre, bf16_t* hn, int lane) {
;     if (hasy) { f32x4 t[4]; float s = 0.f;
; #pragma unroll
;         for (int j = 0; j < 2; ++j) { const u32x4 w = R.y[j];
;             t[2 * j] = (f32x4){bf2f(w.x & 0xffff), bf2f(w.x >> 16), bf2f(w.y & 0xffff), bf2f(w.y >> 16)}; t[2 * j + 1] = (f32x4){bf2f(w.z & 0xffff), bf2f(w.z >> 16), bf2f(w.w & 0xffff), bf2f(w.w >> 16)}; }
; #pragma unroll
;         for (int j = 0; j < 4; ++j) s += (t[j][0] * t[j][0] + t[j][1] * t[j][1]) + (t[j][2] * t[j][2] + t[j][3] * t[j][3]);
;         const float rs = rsqrtf(wave_sum(s) * (1.f / DM) + 1e-6f) * scale;
; #pragma unroll
;         for (int j = 0; j < 4; ++j) { const f32x4 g = *(const f32x4*)(gpost + 512 * (j >> 1) + 8 * lane + 4 * (j & 1)); R.v[j] = R.v[j] + t[j] * g * rs; } }
;     if (xo) {
; #pragma unroll
;         for (int j = 0; j < 4; ++j) __builtin_nontemporal_store(R.v[j], (f32x4*)(xo + 512 * (j >> 1) + 8 * lane + 4 * (j & 1))); }
;     if (hn) { float s = 0.f;
; #pragma unroll
;         for (int j = 0; j < 4; ++j) s += (R.v[j][0] * R.v[j][0] + R.v[j][1] * R.v[j][1]) + (R.v[j][2] * R.v[j][2] + R.v[j][3] * R.v[j][3]);
;         const float rs = rsqrtf(wave_sum(s) * (1.f / DM) + 1e-6f);
; #pragma unroll
;         for (int j = 0; j < 2; ++j) { const f32x4 g0 = *(const f32x4*)(gpre + 512 * j + 8 * lane), g1 = *(const f32x4*)(gpre + 512 * j + 8 * lane + 4); const f32x4 o0 = R.v[2 * j] * g0 * rs, o1 = R.v[2 * j + 1] * g1 * rs;
;             u32x4 w; w.x = cvt_pk_bf16(o0[0], o0[1]); w.y = cvt_pk_bf16(o0[2], o0[3]); w.z = cvt_pk_bf16(o1[0], o1[1]); w.w = cvt_pk_bf16(o1[2], o1[3]); *(u32x4*)(hn + 512 * j + 8 * lane) = w; } }
.Lrn_loop:
	s_mul_i32 s25, s44, 3
	s_add_i32 s25, s25, s24
	s_cmp_lt_i32 s25, 0x10000
	s_cselect_b32 s25, s25, s24
	s_lshl_b32 s34, s25, 12
	s_lshl_b32 s4, s25, 11
	v_lshl_add_u64 v[228:229], v[62:63], 0, s[34:35]
	v_lshl_add_u64 v[230:231], v[52:53], 0, s[4:5]
	global_load_dwordx4 v[162:165], v[228:229], off nt
	global_load_dwordx4 v[166:169], v[228:229], off offset:1024 nt
	global_load_dwordx4 v[170:173], v[228:229], off offset:2048 nt
	global_load_dwordx4 v[174:177], v[228:229], off offset:3072 nt
	global_load_dwordx2 v[178:179], v[230:231], off nt
	global_load_dwordx2 v[180:181], v[230:231], off offset:512 nt
	global_load_dwordx2 v[182:183], v[230:231], off offset:1024 nt
	global_load_dwordx2 v[184:185], v[230:231], off offset:1536 nt
	s_lshl_b32 s18, s24, 12
	s_lshl_b32 s28, s24, 11
	s_andn2_b64 vcc, exec, s[40:41]
	s_waitcnt vmcnt(36)
	v_lshlrev_b32_e32 v206, 16, v18
	v_and_b32_e32 v207, 0xffff0000, v18
	v_lshlrev_b32_e32 v208, 16, v19
	v_and_b32_e32 v209, 0xffff0000, v19
	v_lshlrev_b32_e32 v210, 16, v20
	v_and_b32_e32 v211, 0xffff0000, v20
	v_lshlrev_b32_e32 v212, 16, v21
	v_and_b32_e32 v213, 0xffff0000, v21
	v_lshlrev_b32_e32 v214, 16, v22
	v_and_b32_e32 v215, 0xffff0000, v22
	v_lshlrev_b32_e32 v216, 16, v23
	v_and_b32_e32 v217, 0xffff0000, v23
	v_lshlrev_b32_e32 v218, 16, v24
	v_and_b32_e32 v219, 0xffff0000, v24
	v_lshlrev_b32_e32 v220, 16, v25
	v_and_b32_e32 v221, 0xffff0000, v25
	v_pk_mul_f32 v[222:223], v[206:207], v[206:207]
	v_pk_fma_f32 v[222:223], v[208:209], v[208:209], v[222:223]
	v_pk_fma_f32 v[222:223], v[210:211], v[210:211], v[222:223]
	v_pk_fma_f32 v[222:223], v[212:213], v[212:213], v[222:223]
	v_pk_fma_f32 v[222:223], v[214:215], v[214:215], v[222:223]
	v_pk_fma_f32 v[222:223], v[216:217], v[216:217], v[222:223]
	v_pk_fma_f32 v[222:223], v[218:219], v[218:219], v[222:223]
	v_pk_fma_f32 v[222:223], v[220:221], v[220:221], v[222:223]
	v_lshl_add_u64 v[228:229], v[56:57], 0, s[18:19]
	v_add_f32_e32 v224, v222, v223
	s_nop 1
	v_add_f32_dpp v224, v224, v224 quad_perm:[1,0,3,2] row_mask:0xf bank_mask:0xf bound_ctrl:1
	s_nop 1
	v_add_f32_dpp v224, v224, v224 quad_perm:[2,3,0,1] row_mask:0xf bank_mask:0xf bound_ctrl:1
	s_nop 1
	v_add_f32_dpp v224, v224, v224 row_half_mirror row_mask:0xf bank_mask:0xf bound_ctrl:1
	s_nop 1
	v_add_f32_dpp v224, v224, v224 row_mirror row_mask:0xf bank_mask:0xf bound_ctrl:1
	v_mov_b32_e32 v225, v224
	s_nop 1
	v_permlane16_swap_b32_e32 v224, v225
	v_add_f32_e32 v224, v224, v225
	v_mov_b32_e32 v225, v224
	s_nop 1
	v_permlane32_swap_b32_e32 v224, v225
	v_add_f32_e32 v224, v224, v225
	v_fmamk_f32 v224, v224, 0x3a800000, v197
	v_rsq_f32_e32 v224, v224
	v_lshl_add_u64 v[230:231], v[60:61], 0, s[28:29]
	v_mul_f32_e32 v226, v69, v224
	v_pk_mul_f32 v[206:207], v[206:207], v[96:97]
	v_pk_mul_f32 v[208:209], v[208:209], v[98:99]
	v_pk_mul_f32 v[210:211], v[210:211], v[100:101]
	v_pk_mul_f32 v[212:213], v[212:213], v[102:103]
	v_pk_mul_f32 v[214:215], v[214:215], v[104:105]
	v_pk_mul_f32 v[216:217], v[216:217], v[106:107]
	v_pk_mul_f32 v[218:219], v[218:219], v[108:109]
	v_pk_mul_f32 v[220:221], v[220:221], v[110:111]
	v_pk_fma_f32 v[2:3], v[206:207], v[226:227], v[2:3] op_sel_hi:[1,0,1]
	v_pk_fma_f32 v[4:5], v[208:209], v[226:227], v[4:5] op_sel_hi:[1,0,1]
	v_pk_fma_f32 v[6:7], v[210:211], v[226:227], v[6:7] op_sel_hi:[1,0,1]
	v_pk_fma_f32 v[8:9], v[212:213], v[226:227], v[8:9] op_sel_hi:[1,0,1]
	v_pk_fma_f32 v[10:11], v[214:215], v[226:227], v[10:11] op_sel_hi:[1,0,1]
	v_pk_fma_f32 v[12:13], v[216:217], v[226:227], v[12:13] op_sel_hi:[1,0,1]
	v_pk_fma_f32 v[14:15], v[218:219], v[226:227], v[14:15] op_sel_hi:[1,0,1]
	v_pk_fma_f32 v[16:17], v[220:221], v[226:227], v[16:17] op_sel_hi:[1,0,1]
	global_store_dwordx4 v[228:229], v[2:5], off nt
	global_store_dwordx4 v[228:229], v[6:9], off offset:1024 nt
	global_store_dwordx4 v[228:229], v[10:13], off offset:2048 nt
	global_store_dwordx4 v[228:229], v[14:17], off offset:3072 nt
	s_cbranch_vccnz .Lrn_skip0
	v_pk_mul_f32 v[222:223], v[2:3], v[2:3]
	v_pk_fma_f32 v[222:223], v[4:5], v[4:5], v[222:223]
	v_pk_fma_f32 v[222:223], v[6:7], v[6:7], v[222:223]
	v_pk_fma_f32 v[222:223], v[8:9], v[8:9], v[222:223]
	v_pk_fma_f32 v[222:223], v[10:11], v[10:11], v[222:223]
	v_pk_fma_f32 v[222:223], v[12:13], v[12:13], v[222:223]
	v_pk_fma_f32 v[222:223], v[14:15], v[14:15], v[222:223]
	v_pk_fma_f32 v[222:223], v[16:17], v[16:17], v[222:223]
	v_pk_mul_f32 v[232:233], v[2:3], v[112:113]
	v_pk_mul_f32 v[234:235], v[4:5], v[114:115]
	v_pk_mul_f32 v[236:237], v[6:7], v[116:117]
	v_pk_mul_f32 v[238:239], v[8:9], v[118:119]
	v_pk_mul_f32 v[240:241], v[10:11], v[120:121]
	v_pk_mul_f32 v[242:243], v[12:13], v[122:123]
	v_pk_mul_f32 v[244:245], v[14:15], v[124:125]
	v_pk_mul_f32 v[246:247], v[16:17], v[126:127]
	v_add_f32_e32 v224, v222, v223
	s_nop 1
	v_add_f32_dpp v224, v224, v224 quad_perm:[1,0,3,2] row_mask:0xf bank_mask:0xf bound_ctrl:1
	s_nop 1
	v_add_f32_dpp v224, v224, v224 quad_perm:[2,3,0,1] row_mask:0xf bank_mask:0xf bound_ctrl:1
	s_nop 1
	v_add_f32_dpp v224, v224, v224 row_half_mirror row_mask:0xf bank_mask:0xf bound_ctrl:1
	s_nop 1
	v_add_f32_dpp v224, v224, v224 row_mirror row_mask:0xf bank_mask:0xf bound_ctrl:1
	v_mov_b32_e32 v225, v224
	s_nop 1
	v_permlane16_swap_b32_e32 v224, v225
	v_add_f32_e32 v224, v224, v225
	v_mov_b32_e32 v225, v224
	s_nop 1
	v_permlane32_swap_b32_e32 v224, v225
	v_add_f32_e32 v224, v224, v225
	v_fmamk_f32 v224, v224, 0x3a800000, v197
	v_rsq_f32_e32 v226, v224
	s_nop 0
	v_pk_mul_f32 v[232:233], v[232:233], v[226:227] op_sel_hi:[1,0]
	v_pk_mul_f32 v[234:235], v[234:235], v[226:227] op_sel_hi:[1,0]
	v_pk_mul_f32 v[236:237], v[236:237], v[226:227] op_sel_hi:[1,0]
	v_pk_mul_f32 v[238:239], v[238:239], v[226:227] op_sel_hi:[1,0]
	v_pk_mul_f32 v[240:241], v[240:241], v[226:227] op_sel_hi:[1,0]
	v_pk_mul_f32 v[242:243], v[242:243], v[226:227] op_sel_hi:[1,0]
	v_pk_mul_f32 v[244:245], v[244:245], v[226:227] op_sel_hi:[1,0]
	v_pk_mul_f32 v[246:247], v[246:247], v[226:227] op_sel_hi:[1,0]
	v_cvt_pk_bf16_f32 v248, v232, v233
	v_cvt_pk_bf16_f32 v249, v234, v235
	global_store_dwordx2 v[230:231], v[248:249], off offset:0
	v_cvt_pk_bf16_f32 v250, v236, v237
	v_cvt_pk_bf16_f32 v251, v238, v239
	global_store_dwordx2 v[230:231], v[250:251], off offset:512
	v_cvt_pk_bf16_f32 v248, v240, v241
	v_cvt_pk_bf16_f32 v249, v242, v243
	global_store_dwordx2 v[230:231], v[248:249], off offset:1024
	v_cvt_pk_bf16_f32 v250, v244, v245
	v_cvt_pk_bf16_f32 v251, v246, v247
	global_store_dwordx2 v[230:231], v[250:251], off offset:1536
; __device__ __forceinline__ unsigned cvt_pk_bf16(float lo, float hi) { unsigned r; asm volatile("v_cvt_pk_bf16_f32 %0, %1, %2" : "=v"(r) : "v"(lo), "v"(hi)); return r; }
; __device__ __forceinline__ float bf2f(unsigned short b) { return __uint_as_float(((unsigned)b) << 16); }
; __device__ __forceinline__ void rn_finish(RowRegs& R, bool hasy, const float* gpost, float scale, float* xo, const float* gpre, bf16_t* hn, int lane) {
;     if (hasy) { f32x4 t[4]; float s = 0.f;
; #pragma unroll
;         for (int j = 0; j < 2; ++j) { const u32x4 w = R.y[j];
;             t[2 * j] = (f32x4){bf2f(w.x & 0xffff), bf2f(w.x >> 16), bf2f(w.y & 0xffff), bf2f(w.y >> 16)}; t[2 * j + 1] = (f32x4){bf2f(w.z & 0xffff), bf2f(w.z >> 16), bf2f(w.w & 0xffff), bf2f(w.w >> 16)}; }
; #pragma unroll
;         for (int j = 0; j < 4; ++j) s += (t[j][0] * t[j][0] + t[j][1] * t[j][1]) + (t[j][2] * t[j][2] + t[j][3] * t[j][3]);
;         const float rs = rsqrtf(wave_sum(s) * (1.f / DM) + 1e-6f) * scale;
; #pragma unroll
;         for (int j = 0; j < 4; ++j) { const f32x4 g = *(const f32x4*)(gpost + 512 * (j >> 1) + 8 * lane + 4 * (j & 1)); R.v[j] = R.v[j] + t[j] * g * rs; } }
;     if (xo) {
; #pragma unroll
;         for (int j = 0; j < 4; ++j) __builtin_nontemporal_store(R.v[j], (f32x4*)(xo + 512 * (j >> 1) + 8 * lane + 4 * (j & 1))); }
;     if (hn) { float s = 0.f;
; #pragma unroll
;         for (int j = 0; j < 4; ++j) s += (R.v[j][0] * R.v[j][0] + R.v[j][1] * R.v[j][1]) + (R.v[j][2] * R.v[j][2] + R.v[j][3] * R.v[j][3]);
;         const float rs = rsqrtf(wave_sum(s) * (1.f / DM) + 1e-6f);
; #pragma unroll
;         for (int j = 0; j < 2; ++j) { const f32x4 g0 = *(const f32x4*)(gpre + 512 * j + 8 * lane), g1 = *(const f32x4*)(gpre + 512 * j + 8 * lane + 4); const f32x4 o0 = R.v[2 * j] * g0 * rs, o1 = R.v[2 * j + 1] * g1 * rs;
;             u32x4 w; w.x = cvt_pk_bf16(o0[0], o0[1]); w.y = cvt_pk_bf16(o0[2], o0[3]); w.z = cvt_pk_bf16(o1[0], o1[1]); w.w = cvt_pk_bf16(o1[2], o1[3]); *(u32x4*)(hn + 512 * j + 8 * lane) = w; } }
.Lrn_skip0:
	s_add_i32 s24, s24, s44
	s_cmp_gt_i32 s24, 0xffff
	s_cbranch_scc1 .Lrn_exit
	s_mul_i32 s25, s44, 3
	s_add_i32 s25, s25, s24
	s_cmp_lt_i32 s25, 0x10000
	s_cselect_b32 s25, s25, s24
	s_lshl_b32 s34, s25, 12
	s_lshl_b32 s4, s25, 11
	v_lshl_add_u64 v[228:229], v[62:63], 0, s[34:35]
	v_lshl_add_u64 v[230:231], v[52:53], 0, s[4:5]
	global_load_dwordx4 v[2:5], v[228:229], off nt
	global_load_dwordx4 v[6:9], v[228:229], off offset:1024 nt
	global_load_dwordx4 v[10:13], v[228:229], off offset:2048 nt
	global_load_dwordx4 v[14:17], v[228:229], off offset:3072 nt
	global_load_dwordx2 v[18:19], v[230:231], off nt
	global_load_dwordx2 v[20:21], v[230:231], off offset:512 nt
	global_load_dwordx2 v[22:23], v[230:231], off offset:1024 nt
	global_load_dwordx2 v[24:25], v[230:231], off offset:1536 nt
	s_lshl_b32 s18, s24, 12
	s_lshl_b32 s28, s24, 11
	s_andn2_b64 vcc, exec, s[40:41]
	s_waitcnt vmcnt(36)
	v_lshlrev_b32_e32 v206, 16, v42
	v_and_b32_e32 v207, 0xffff0000, v42
	v_lshlrev_b32_e32 v208, 16, v43
	v_and_b32_e32 v209, 0xffff0000, v43
	v_lshlrev_b32_e32 v210, 16, v44
	v_and_b32_e32 v211, 0xffff0000, v44
	v_lshlrev_b32_e32 v212, 16, v45
	v_and_b32_e32 v213, 0xffff0000, v45
	v_lshlrev_b32_e32 v214, 16, v46
	v_and_b32_e32 v215, 0xffff0000, v46
	v_lshlrev_b32_e32 v216, 16, v47
	v_and_b32_e32 v217, 0xffff0000, v47
	v_lshlrev_b32_e32 v218, 16, v48
	v_and_b32_e32 v219, 0xffff0000, v48
	v_lshlrev_b32_e32 v220, 16, v49
	v_and_b32_e32 v221, 0xffff0000, v49
	v_pk_mul_f32 v[222:223], v[206:207], v[206:207]
	v_pk_fma_f32 v[222:223], v[208:209], v[208:209], v[222:223]
	v_pk_fma_f32 v[222:223], v[210:211], v[210:211], v[222:223]
	v_pk_fma_f32 v[222:223], v[212:213], v[212:213], v[222:223]
	v_pk_fma_f32 v[222:223], v[214:215], v[214:215], v[222:223]
	v_pk_fma_f32 v[222:223], v[216:217], v[216:217], v[222:223]
	v_pk_fma_f32 v[222:223], v[218:219], v[218:219], v[222:223]
	v_pk_fma_f32 v[222:223], v[220:221], v[220:221], v[222:223]
	v_lshl_add_u64 v[228:229], v[56:57], 0, s[18:19]
	v_add_f32_e32 v224, v222, v223
	s_nop 1
	v_add_f32_dpp v224, v224, v224 quad_perm:[1,0,3,2] row_mask:0xf bank_mask:0xf bound_ctrl:1
	s_nop 1
	v_add_f32_dpp v224, v224, v224 quad_perm:[2,3,0,1] row_mask:0xf bank_mask:0xf bound_ctrl:1
	s_nop 1
	v_add_f32_dpp v224, v224, v224 row_half_mirror row_mask:0xf bank_mask:0xf bound_ctrl:1
	s_nop 1
	v_add_f32_dpp v224, v224, v224 row_mirror row_mask:0xf bank_mask:0xf bound_ctrl:1
	v_mov_b32_e32 v225, v224
	s_nop 1
	v_permlane16_swap_b32_e32 v224, v225
	v_add_f32_e32 v224, v224, v225
	v_mov_b32_e32 v225, v224
	s_nop 1
	v_permlane32_swap_b32_e32 v224, v225
	v_add_f32_e32 v224, v224, v225
	v_fmamk_f32 v224, v224, 0x3a800000, v197
	v_rsq_f32_e32 v224, v224
	v_lshl_add_u64 v[230:231], v[60:61], 0, s[28:29]
	v_mul_f32_e32 v226, v69, v224
	v_pk_mul_f32 v[206:207], v[206:207], v[96:97]
	v_pk_mul_f32 v[208:209], v[208:209], v[98:99]
	v_pk_mul_f32 v[210:211], v[210:211], v[100:101]
	v_pk_mul_f32 v[212:213], v[212:213], v[102:103]
	v_pk_mul_f32 v[214:215], v[214:215], v[104:105]
	v_pk_mul_f32 v[216:217], v[216:217], v[106:107]
	v_pk_mul_f32 v[218:219], v[218:219], v[108:109]
	v_pk_mul_f32 v[220:221], v[220:221], v[110:111]
	v_pk_fma_f32 v[26:27], v[206:207], v[226:227], v[26:27] op_sel_hi:[1,0,1]
	v_pk_fma_f32 v[28:29], v[208:209], v[226:227], v[28:29] op_sel_hi:[1,0,1]
	v_pk_fma_f32 v[30:31], v[210:211], v[226:227], v[30:31] op_sel_hi:[1,0,1]
	v_pk_fma_f32 v[32:33], v[212:213], v[226:227], v[32:33] op_sel_hi:[1,0,1]
	v_pk_fma_f32 v[34:35], v[214:215], v[226:227], v[34:35] op_sel_hi:[1,0,1]
	v_pk_fma_f32 v[36:37], v[216:217], v[226:227], v[36:37] op_sel_hi:[1,0,1]
	v_pk_fma_f32 v[38:39], v[218:219], v[226:227], v[38:39] op_sel_hi:[1,0,1]
	v_pk_fma_f32 v[40:41], v[220:221], v[226:227], v[40:41] op_sel_hi:[1,0,1]
	global_store_dwordx4 v[228:229], v[26:29], off nt
	global_store_dwordx4 v[228:229], v[30:33], off offset:1024 nt
	global_store_dwordx4 v[228:229], v[34:37], off offset:2048 nt
	global_store_dwordx4 v[228:229], v[38:41], off offset:3072 nt
	s_cbranch_vccnz .Lrn_skip1
	v_pk_mul_f32 v[222:223], v[26:27], v[26:27]
	v_pk_fma_f32 v[222:223], v[28:29], v[28:29], v[222:223]
	v_pk_fma_f32 v[222:223], v[30:31], v[30:31], v[222:223]
	v_pk_fma_f32 v[222:223], v[32:33], v[32:33], v[222:223]
	v_pk_fma_f32 v[222:223], v[34:35], v[34:35], v[222:223]
	v_pk_fma_f32 v[222:223], v[36:37], v[36:37], v[222:223]
	v_pk_fma_f32 v[222:223], v[38:39], v[38:39], v[222:223]
	v_pk_fma_f32 v[222:223], v[40:41], v[40:41], v[222:223]
	v_pk_mul_f32 v[232:233], v[26:27], v[112:113]
	v_pk_mul_f32 v[234:235], v[28:29], v[114:115]
	v_pk_mul_f32 v[236:237], v[30:31], v[116:117]
	v_pk_mul_f32 v[238:239], v[32:33], v[118:119]
	v_pk_mul_f32 v[240:241], v[34:35], v[120:121]
	v_pk_mul_f32 v[242:243], v[36:37], v[122:123]
	v_pk_mul_f32 v[244:245], v[38:39], v[124:125]
	v_pk_mul_f32 v[246:247], v[40:41], v[126:127]
	v_add_f32_e32 v224, v222, v223
	s_nop 1
	v_add_f32_dpp v224, v224, v224 quad_perm:[1,0,3,2] row_mask:0xf bank_mask:0xf bound_ctrl:1
	s_nop 1
	v_add_f32_dpp v224, v224, v224 quad_perm:[2,3,0,1] row_mask:0xf bank_mask:0xf bound_ctrl:1
	s_nop 1
	v_add_f32_dpp v224, v224, v224 row_half_mirror row_mask:0xf bank_mask:0xf bound_ctrl:1
	s_nop 1
	v_add_f32_dpp v224, v224, v224 row_mirror row_mask:0xf bank_mask:0xf bound_ctrl:1
	v_mov_b32_e32 v225, v224
	s_nop 1
	v_permlane16_swap_b32_e32 v224, v225
	v_add_f32_e32 v224, v224, v225
	v_mov_b32_e32 v225, v224
	s_nop 1
	v_permlane32_swap_b32_e32 v224, v225
	v_add_f32_e32 v224, v224, v225
	v_fmamk_f32 v224, v224, 0x3a800000, v197
	v_rsq_f32_e32 v226, v224
	s_nop 0
	v_pk_mul_f32 v[232:233], v[232:233], v[226:227] op_sel_hi:[1,0]
	v_pk_mul_f32 v[234:235], v[234:235], v[226:227] op_sel_hi:[1,0]
	v_pk_mul_f32 v[236:237], v[236:237], v[226:227] op_sel_hi:[1,0]
	v_pk_mul_f32 v[238:239], v[238:239], v[226:227] op_sel_hi:[1,0]
	v_pk_mul_f32 v[240:241], v[240:241], v[226:227] op_sel_hi:[1,0]
	v_pk_mul_f32 v[242:243], v[242:243], v[226:227] op_sel_hi:[1,0]
	v_pk_mul_f32 v[244:245], v[244:245], v[226:227] op_sel_hi:[1,0]
	v_pk_mul_f32 v[246:247], v[246:247], v[226:227] op_sel_hi:[1,0]
	v_cvt_pk_bf16_f32 v248, v232, v233
	v_cvt_pk_bf16_f32 v249, v234, v235
	global_store_dwordx2 v[230:231], v[248:249], off offset:0
	v_cvt_pk_bf16_f32 v250, v236, v237
	v_cvt_pk_bf16_f32 v251, v238, v239
	global_store_dwordx2 v[230:231], v[250:251], off offset:512
	v_cvt_pk_bf16_f32 v248, v240, v241
	v_cvt_pk_bf16_f32 v249, v242, v243
	global_store_dwordx2 v[230:231], v[248:249], off offset:1024
	v_cvt_pk_bf16_f32 v250, v244, v245
	v_cvt_pk_bf16_f32 v251, v246, v247
	global_store_dwordx2 v[230:231], v[250:251], off offset:1536
; __device__ __forceinline__ unsigned cvt_pk_bf16(float lo, float hi) { unsigned r; asm volatile("v_cvt_pk_bf16_f32 %0, %1, %2" : "=v"(r) : "v"(lo), "v"(hi)); return r; }
; __device__ __forceinline__ float bf2f(unsigned short b) { return __uint_as_float(((unsigned)b) << 16); }
; __device__ __forceinline__ void rn_finish(RowRegs& R, bool hasy, const float* gpost, float scale, float* xo, const float* gpre, bf16_t* hn, int lane) {
;     if (hasy) { f32x4 t[4]; float s = 0.f;
; #pragma unroll
;         for (int j = 0; j < 2; ++j) { const u32x4 w = R.y[j];
;             t[2 * j] = (f32x4){bf2f(w.x & 0xffff), bf2f(w.x >> 16), bf2f(w.y & 0xffff), bf2f(w.y >> 16)}; t[2 * j + 1] = (f32x4){bf2f(w.z & 0xffff), bf2f(w.z >> 16), bf2f(w.w & 0xffff), bf2f(w.w >> 16)}; }
; #pragma unroll
;         for (int j = 0; j < 4; ++j) s += (t[j][0] * t[j][0] + t[j][1] * t[j][1]) + (t[j][2] * t[j][2] + t[j][3] * t[j][3]);
;         const float rs = rsqrtf(wave_sum(s) * (1.f / DM) + 1e-6f) * scale;
; #pragma unroll
;         for (int j = 0; j < 4; ++j) { const f32x4 g = *(const f32x4*)(gpost + 512 * (j >> 1) + 8 * lane + 4 * (j & 1)); R.v[j] = R.v[j] + t[j] * g * rs; } }
;     if (xo) {
; #pragma unroll
;         for (int j = 0; j < 4; ++j) __builtin_nontemporal_store(R.v[j], (f32x4*)(xo + 512 * (j >> 1) + 8 * lane + 4 * (j & 1))); }
;     if (hn) { float s = 0.f;
; #pragma unroll
;         for (int j = 0; j < 4; ++j) s += (R.v[j][0] * R.v[j][0] + R.v[j][1] * R.v[j][1]) + (R.v[j][2] * R.v[j][2] + R.v[j][3] * R.v[j][3]);
;         const float rs = rsqrtf(wave_sum(s) * (1.f / DM) + 1e-6f);
; #pragma unroll
;         for (int j = 0; j < 2; ++j) { const f32x4 g0 = *(const f32x4*)(gpre + 512 * j + 8 * lane), g1 = *(const f32x4*)(gpre + 512 * j + 8 * lane + 4); const f32x4 o0 = R.v[2 * j] * g0 * rs, o1 = R.v[2 * j + 1] * g1 * rs;
;             u32x4 w; w.x = cvt_pk_bf16(o0[0], o0[1]); w.y = cvt_pk_bf16(o0[2], o0[3]); w.z = cvt_pk_bf16(o1[0], o1[1]); w.w = cvt_pk_bf16(o1[2], o1[3]); *(u32x4*)(hn + 512 * j + 8 * lane) = w; } }
.Lrn_skip1:
	s_add_i32 s24, s24, s44
	s_cmp_gt_i32 s24, 0xffff
	s_cbranch_scc1 .Lrn_exit
	s_mul_i32 s25, s44, 3
	s_add_i32 s25, s25, s24
	s_cmp_lt_i32 s25, 0x10000
	s_cselect_b32 s25, s25, s24
	s_lshl_b32 s34, s25, 12
	s_lshl_b32 s4, s25, 11
	v_lshl_add_u64 v[228:229], v[62:63], 0, s[34:35]
	v_lshl_add_u64 v[230:231], v[52:53], 0, s[4:5]
	global_load_dwordx4 v[26:29], v[228:229], off nt
	global_load_dwordx4 v[30:33], v[228:229], off offset:1024 nt
	global_load_dwordx4 v[34:37], v[228:229], off offset:2048 nt
	global_load_dwordx4 v[38:41], v[228:229], off offset:3072 nt
	global_load_dwordx2 v[42:43], v[230:231], off nt
	global_load_dwordx2 v[44:45], v[230:231], off offset:512 nt
	global_load_dwordx2 v[46:47], v[230:231], off offset:1024 nt
	global_load_dwordx2 v[48:49], v[230:231], off offset:1536 nt
	s_lshl_b32 s18, s24, 12
	s_lshl_b32 s28, s24, 11
	s_andn2_b64 vcc, exec, s[40:41]
	s_waitcnt vmcnt(36)
	v_lshlrev_b32_e32 v206, 16, v86
	v_and_b32_e32 v207, 0xffff0000, v86
	v_lshlrev_b32_e32 v208, 16, v87
	v_and_b32_e32 v209, 0xffff0000, v87
	v_lshlrev_b32_e32 v210, 16, v88
	v_and_b32_e32 v211, 0xffff0000, v88
	v_lshlrev_b32_e32 v212, 16, v89
	v_and_b32_e32 v213, 0xffff0000, v89
	v_lshlrev_b32_e32 v214, 16, v90
	v_and_b32_e32 v215, 0xffff0000, v90
	v_lshlrev_b32_e32 v216, 16, v91
	v_and_b32_e32 v217, 0xffff0000, v91
	v_lshlrev_b32_e32 v218, 16, v92
	v_and_b32_e32 v219, 0xffff0000, v92
	v_lshlrev_b32_e32 v220, 16, v93
	v_and_b32_e32 v221, 0xffff0000, v93
	v_pk_mul_f32 v[222:223], v[206:207], v[206:207]
	v_pk_fma_f32 v[222:223], v[208:209], v[208:209], v[222:223]
	v_pk_fma_f32 v[222:223], v[210:211], v[210:211], v[222:223]
	v_pk_fma_f32 v[222:223], v[212:213], v[212:213], v[222:223]
	v_pk_fma_f32 v[222:223], v[214:215], v[214:215], v[222:223]
	v_pk_fma_f32 v[222:223], v[216:217], v[216:217], v[222:223]
	v_pk_fma_f32 v[222:223], v[218:219], v[218:219], v[222:223]
	v_pk_fma_f32 v[222:223], v[220:221], v[220:221], v[222:223]
	v_lshl_add_u64 v[228:229], v[56:57], 0, s[18:19]
	v_add_f32_e32 v224, v222, v223
	s_nop 1
	v_add_f32_dpp v224, v224, v224 quad_perm:[1,0,3,2] row_mask:0xf bank_mask:0xf bound_ctrl:1
	s_nop 1
	v_add_f32_dpp v224, v224, v224 quad_perm:[2,3,0,1] row_mask:0xf bank_mask:0xf bound_ctrl:1
	s_nop 1
	v_add_f32_dpp v224, v224, v224 row_half_mirror row_mask:0xf bank_mask:0xf bound_ctrl:1
	s_nop 1
	v_add_f32_dpp v224, v224, v224 row_mirror row_mask:0xf bank_mask:0xf bound_ctrl:1
	v_mov_b32_e32 v225, v224
	s_nop 1
	v_permlane16_swap_b32_e32 v224, v225
	v_add_f32_e32 v224, v224, v225
	v_mov_b32_e32 v225, v224
	s_nop 1
	v_permlane32_swap_b32_e32 v224, v225
	v_add_f32_e32 v224, v224, v225
	v_fmamk_f32 v224, v224, 0x3a800000, v197
	v_rsq_f32_e32 v224, v224
	v_lshl_add_u64 v[230:231], v[60:61], 0, s[28:29]
	v_mul_f32_e32 v226, v69, v224
	v_pk_mul_f32 v[206:207], v[206:207], v[96:97]
	v_pk_mul_f32 v[208:209], v[208:209], v[98:99]
	v_pk_mul_f32 v[210:211], v[210:211], v[100:101]
	v_pk_mul_f32 v[212:213], v[212:213], v[102:103]
	v_pk_mul_f32 v[214:215], v[214:215], v[104:105]
	v_pk_mul_f32 v[216:217], v[216:217], v[106:107]
	v_pk_mul_f32 v[218:219], v[218:219], v[108:109]
	v_pk_mul_f32 v[220:221], v[220:221], v[110:111]
	v_pk_fma_f32 v[70:71], v[206:207], v[226:227], v[70:71] op_sel_hi:[1,0,1]
	v_pk_fma_f32 v[72:73], v[208:209], v[226:227], v[72:73] op_sel_hi:[1,0,1]
	v_pk_fma_f32 v[74:75], v[210:211], v[226:227], v[74:75] op_sel_hi:[1,0,1]
	v_pk_fma_f32 v[76:77], v[212:213], v[226:227], v[76:77] op_sel_hi:[1,0,1]
	v_pk_fma_f32 v[78:79], v[214:215], v[226:227], v[78:79] op_sel_hi:[1,0,1]
	v_pk_fma_f32 v[80:81], v[216:217], v[226:227], v[80:81] op_sel_hi:[1,0,1]
	v_pk_fma_f32 v[82:83], v[218:219], v[226:227], v[82:83] op_sel_hi:[1,0,1]
	v_pk_fma_f32 v[84:85], v[220:221], v[226:227], v[84:85] op_sel_hi:[1,0,1]
	global_store_dwordx4 v[228:229], v[70:73], off nt
	global_store_dwordx4 v[228:229], v[74:77], off offset:1024 nt
	global_store_dwordx4 v[228:229], v[78:81], off offset:2048 nt
	global_store_dwordx4 v[228:229], v[82:85], off offset:3072 nt
	s_cbranch_vccnz .Lrn_skip2
	v_pk_mul_f32 v[222:223], v[70:71], v[70:71]
	v_pk_fma_f32 v[222:223], v[72:73], v[72:73], v[222:223]
	v_pk_fma_f32 v[222:223], v[74:75], v[74:75], v[222:223]
	v_pk_fma_f32 v[222:223], v[76:77], v[76:77], v[222:223]
	v_pk_fma_f32 v[222:223], v[78:79], v[78:79], v[222:223]
	v_pk_fma_f32 v[222:223], v[80:81], v[80:81], v[222:223]
	v_pk_fma_f32 v[222:223], v[82:83], v[82:83], v[222:223]
	v_pk_fma_f32 v[222:223], v[84:85], v[84:85], v[222:223]
	v_pk_mul_f32 v[232:233], v[70:71], v[112:113]
	v_pk_mul_f32 v[234:235], v[72:73], v[114:115]
	v_pk_mul_f32 v[236:237], v[74:75], v[116:117]
	v_pk_mul_f32 v[238:239], v[76:77], v[118:119]
	v_pk_mul_f32 v[240:241], v[78:79], v[120:121]
	v_pk_mul_f32 v[242:243], v[80:81], v[122:123]
	v_pk_mul_f32 v[244:245], v[82:83], v[124:125]
	v_pk_mul_f32 v[246:247], v[84:85], v[126:127]
	v_add_f32_e32 v224, v222, v223
	s_nop 1
	v_add_f32_dpp v224, v224, v224 quad_perm:[1,0,3,2] row_mask:0xf bank_mask:0xf bound_ctrl:1
	s_nop 1
	v_add_f32_dpp v224, v224, v224 quad_perm:[2,3,0,1] row_mask:0xf bank_mask:0xf bound_ctrl:1
	s_nop 1
	v_add_f32_dpp v224, v224, v224 row_half_mirror row_mask:0xf bank_mask:0xf bound_ctrl:1
	s_nop 1
	v_add_f32_dpp v224, v224, v224 row_mirror row_mask:0xf bank_mask:0xf bound_ctrl:1
	v_mov_b32_e32 v225, v224
	s_nop 1
	v_permlane16_swap_b32_e32 v224, v225
	v_add_f32_e32 v224, v224, v225
	v_mov_b32_e32 v225, v224
	s_nop 1
	v_permlane32_swap_b32_e32 v224, v225
	v_add_f32_e32 v224, v224, v225
	v_fmamk_f32 v224, v224, 0x3a800000, v197
	v_rsq_f32_e32 v226, v224
	s_nop 0
	v_pk_mul_f32 v[232:233], v[232:233], v[226:227] op_sel_hi:[1,0]
	v_pk_mul_f32 v[234:235], v[234:235], v[226:227] op_sel_hi:[1,0]
	v_pk_mul_f32 v[236:237], v[236:237], v[226:227] op_sel_hi:[1,0]
	v_pk_mul_f32 v[238:239], v[238:239], v[226:227] op_sel_hi:[1,0]
	v_pk_mul_f32 v[240:241], v[240:241], v[226:227] op_sel_hi:[1,0]
	v_pk_mul_f32 v[242:243], v[242:243], v[226:227] op_sel_hi:[1,0]
	v_pk_mul_f32 v[244:245], v[244:245], v[226:227] op_sel_hi:[1,0]
	v_pk_mul_f32 v[246:247], v[246:247], v[226:227] op_sel_hi:[1,0]
	v_cvt_pk_bf16_f32 v248, v232, v233
	v_cvt_pk_bf16_f32 v249, v234, v235
	global_store_dwordx2 v[230:231], v[248:249], off offset:0
	v_cvt_pk_bf16_f32 v250, v236, v237
	v_cvt_pk_bf16_f32 v251, v238, v239
	global_store_dwordx2 v[230:231], v[250:251], off offset:512
	v_cvt_pk_bf16_f32 v248, v240, v241
	v_cvt_pk_bf16_f32 v249, v242, v243
	global_store_dwordx2 v[230:231], v[248:249], off offset:1024
	v_cvt_pk_bf16_f32 v250, v244, v245
	v_cvt_pk_bf16_f32 v251, v246, v247
	global_store_dwordx2 v[230:231], v[250:251], off offset:1536
; __device__ __forceinline__ unsigned cvt_pk_bf16(float lo, float hi) { unsigned r; asm volatile("v_cvt_pk_bf16_f32 %0, %1, %2" : "=v"(r) : "v"(lo), "v"(hi)); return r; }
; __device__ __forceinline__ float bf2f(unsigned short b) { return __uint_as_float(((unsigned)b) << 16); }
; __device__ __forceinline__ void rn_finish(RowRegs& R, bool hasy, const float* gpost, float scale, float* xo, const float* gpre, bf16_t* hn, int lane) {
;     if (hasy) { f32x4 t[4]; float s = 0.f;
; #pragma unroll
;         for (int j = 0; j < 2; ++j) { const u32x4 w = R.y[j];
;             t[2 * j] = (f32x4){bf2f(w.x & 0xffff), bf2f(w.x >> 16), bf2f(w.y & 0xffff), bf2f(w.y >> 16)}; t[2 * j + 1] = (f32x4){bf2f(w.z & 0xffff), bf2f(w.z >> 16), bf2f(w.w & 0xffff), bf2f(w.w >> 16)}; }
; #pragma unroll
;         for (int j = 0; j < 4; ++j) s += (t[j][0] * t[j][0] + t[j][1] * t[j][1]) + (t[j][2] * t[j][2] + t[j][3] * t[j][3]);
;         const float rs = rsqrtf(wave_sum(s) * (1.f / DM) + 1e-6f) * scale;
; #pragma unroll
;         for (int j = 0; j < 4; ++j) { const f32x4 g = *(const f32x4*)(gpost + 512 * (j >> 1) + 8 * lane + 4 * (j & 1)); R.v[j] = R.v[j] + t[j] * g * rs; } }
;     if (xo) {
; #pragma unroll
;         for (int j = 0; j < 4; ++j) __builtin_nontemporal_store(R.v[j], (f32x4*)(xo + 512 * (j >> 1) + 8 * lane + 4 * (j & 1))); }
;     if (hn) { float s = 0.f;
; #pragma unroll
;         for (int j = 0; j < 4; ++j) s += (R.v[j][0] * R.v[j][0] + R.v[j][1] * R.v[j][1]) + (R.v[j][2] * R.v[j][2] + R.v[j][3] * R.v[j][3]);
;         const float rs = rsqrtf(wave_sum(s) * (1.f / DM) + 1e-6f);
; #pragma unroll
;         for (int j = 0; j < 2; ++j) { const f32x4 g0 = *(const f32x4*)(gpre + 512 * j + 8 * lane), g1 = *(const f32x4*)(gpre + 512 * j + 8 * lane + 4); const f32x4 o0 = R.v[2 * j] * g0 * rs, o1 = R.v[2 * j + 1] * g1 * rs;
;             u32x4 w; w.x = cvt_pk_bf16(o0[0], o0[1]); w.y = cvt_pk_bf16(o0[2], o0[3]); w.z = cvt_pk_bf16(o1[0], o1[1]); w.w = cvt_pk_bf16(o1[2], o1[3]); *(u32x4*)(hn + 512 * j + 8 * lane) = w; } }
.Lrn_skip2:
	s_add_i32 s24, s24, s44
	s_cmp_gt_i32 s24, 0xffff
	s_cbranch_scc1 .Lrn_exit
	s_mul_i32 s25, s44, 3
	s_add_i32 s25, s25, s24
	s_cmp_lt_i32 s25, 0x10000
	s_cselect_b32 s25, s25, s24
	s_lshl_b32 s34, s25, 12
	s_lshl_b32 s4, s25, 11
	v_lshl_add_u64 v[228:229], v[62:63], 0, s[34:35]
	v_lshl_add_u64 v[230:231], v[52:53], 0, s[4:5]
	global_load_dwordx4 v[70:73], v[228:229], off nt
	global_load_dwordx4 v[74:77], v[228:229], off offset:1024 nt
	global_load_dwordx4 v[78:81], v[228:229], off offset:2048 nt
	global_load_dwordx4 v[82:85], v[228:229], off offset:3072 nt
	global_load_dwordx2 v[86:87], v[230:231], off nt
	global_load_dwordx2 v[88:89], v[230:231], off offset:512 nt
	global_load_dwordx2 v[90:91], v[230:231], off offset:1024 nt
	global_load_dwordx2 v[92:93], v[230:231], off offset:1536 nt
	s_lshl_b32 s18, s24, 12
	s_lshl_b32 s28, s24, 11
	s_andn2_b64 vcc, exec, s[40:41]
	s_waitcnt vmcnt(36)
	v_lshlrev_b32_e32 v206, 16, v178
	v_and_b32_e32 v207, 0xffff0000, v178
	v_lshlrev_b32_e32 v208, 16, v179
	v_and_b32_e32 v209, 0xffff0000, v179
	v_lshlrev_b32_e32 v210, 16, v180
	v_and_b32_e32 v211, 0xffff0000, v180
	v_lshlrev_b32_e32 v212, 16, v181
	v_and_b32_e32 v213, 0xffff0000, v181
	v_lshlrev_b32_e32 v214, 16, v182
	v_and_b32_e32 v215, 0xffff0000, v182
	v_lshlrev_b32_e32 v216, 16, v183
	v_and_b32_e32 v217, 0xffff0000, v183
	v_lshlrev_b32_e32 v218, 16, v184
	v_and_b32_e32 v219, 0xffff0000, v184
	v_lshlrev_b32_e32 v220, 16, v185
	v_and_b32_e32 v221, 0xffff0000, v185
	v_pk_mul_f32 v[222:223], v[206:207], v[206:207]
	v_pk_fma_f32 v[222:223], v[208:209], v[208:209], v[222:223]
	v_pk_fma_f32 v[222:223], v[210:211], v[210:211], v[222:223]
	v_pk_fma_f32 v[222:223], v[212:213], v[212:213], v[222:223]
	v_pk_fma_f32 v[222:223], v[214:215], v[214:215], v[222:223]
	v_pk_fma_f32 v[222:223], v[216:217], v[216:217], v[222:223]
	v_pk_fma_f32 v[222:223], v[218:219], v[218:219], v[222:223]
	v_pk_fma_f32 v[222:223], v[220:221], v[220:221], v[222:223]
	v_lshl_add_u64 v[228:229], v[56:57], 0, s[18:19]
	v_add_f32_e32 v224, v222, v223
	s_nop 1
	v_add_f32_dpp v224, v224, v224 quad_perm:[1,0,3,2] row_mask:0xf bank_mask:0xf bound_ctrl:1
	s_nop 1
	v_add_f32_dpp v224, v224, v224 quad_perm:[2,3,0,1] row_mask:0xf bank_mask:0xf bound_ctrl:1
	s_nop 1
	v_add_f32_dpp v224, v224, v224 row_half_mirror row_mask:0xf bank_mask:0xf bound_ctrl:1
	s_nop 1
	v_add_f32_dpp v224, v224, v224 row_mirror row_mask:0xf bank_mask:0xf bound_ctrl:1
	v_mov_b32_e32 v225, v224
	s_nop 1
	v_permlane16_swap_b32_e32 v224, v225
	v_add_f32_e32 v224, v224, v225
	v_mov_b32_e32 v225, v224
	s_nop 1
	v_permlane32_swap_b32_e32 v224, v225
	v_add_f32_e32 v224, v224, v225
	v_fmamk_f32 v224, v224, 0x3a800000, v197
	v_rsq_f32_e32 v224, v224
	v_lshl_add_u64 v[230:231], v[60:61], 0, s[28:29]
	v_mul_f32_e32 v226, v69, v224
	v_pk_mul_f32 v[206:207], v[206:207], v[96:97]
	v_pk_mul_f32 v[208:209], v[208:209], v[98:99]
	v_pk_mul_f32 v[210:211], v[210:211], v[100:101]
	v_pk_mul_f32 v[212:213], v[212:213], v[102:103]
	v_pk_mul_f32 v[214:215], v[214:215], v[104:105]
	v_pk_mul_f32 v[216:217], v[216:217], v[106:107]
	v_pk_mul_f32 v[218:219], v[218:219], v[108:109]
	v_pk_mul_f32 v[220:221], v[220:221], v[110:111]
	v_pk_fma_f32 v[162:163], v[206:207], v[226:227], v[162:163] op_sel_hi:[1,0,1]
	v_pk_fma_f32 v[164:165], v[208:209], v[226:227], v[164:165] op_sel_hi:[1,0,1]
	v_pk_fma_f32 v[166:167], v[210:211], v[226:227], v[166:167] op_sel_hi:[1,0,1]
	v_pk_fma_f32 v[168:169], v[212:213], v[226:227], v[168:169] op_sel_hi:[1,0,1]
	v_pk_fma_f32 v[170:171], v[214:215], v[226:227], v[170:171] op_sel_hi:[1,0,1]
	v_pk_fma_f32 v[172:173], v[216:217], v[226:227], v[172:173] op_sel_hi:[1,0,1]
	v_pk_fma_f32 v[174:175], v[218:219], v[226:227], v[174:175] op_sel_hi:[1,0,1]
	v_pk_fma_f32 v[176:177], v[220:221], v[226:227], v[176:177] op_sel_hi:[1,0,1]
	global_store_dwordx4 v[228:229], v[162:165], off nt
	global_store_dwordx4 v[228:229], v[166:169], off offset:1024 nt
	global_store_dwordx4 v[228:229], v[170:173], off offset:2048 nt
	global_store_dwordx4 v[228:229], v[174:177], off offset:3072 nt
	s_cbranch_vccnz .Lrn_skip3
	v_pk_mul_f32 v[222:223], v[162:163], v[162:163]
	v_pk_fma_f32 v[222:223], v[164:165], v[164:165], v[222:223]
	v_pk_fma_f32 v[222:223], v[166:167], v[166:167], v[222:223]
	v_pk_fma_f32 v[222:223], v[168:169], v[168:169], v[222:223]
	v_pk_fma_f32 v[222:223], v[170:171], v[170:171], v[222:223]
	v_pk_fma_f32 v[222:223], v[172:173], v[172:173], v[222:223]
	v_pk_fma_f32 v[222:223], v[174:175], v[174:175], v[222:223]
	v_pk_fma_f32 v[222:223], v[176:177], v[176:177], v[222:223]
	v_pk_mul_f32 v[232:233], v[162:163], v[112:113]
	v_pk_mul_f32 v[234:235], v[164:165], v[114:115]
	v_pk_mul_f32 v[236:237], v[166:167], v[116:117]
	v_pk_mul_f32 v[238:239], v[168:169], v[118:119]
	v_pk_mul_f32 v[240:241], v[170:171], v[120:121]
	v_pk_mul_f32 v[242:243], v[172:173], v[122:123]
	v_pk_mul_f32 v[244:245], v[174:175], v[124:125]
	v_pk_mul_f32 v[246:247], v[176:177], v[126:127]
	v_add_f32_e32 v224, v222, v223
	s_nop 1
	v_add_f32_dpp v224, v224, v224 quad_perm:[1,0,3,2] row_mask:0xf bank_mask:0xf bound_ctrl:1
	s_nop 1
	v_add_f32_dpp v224, v224, v224 quad_perm:[2,3,0,1] row_mask:0xf bank_mask:0xf bound_ctrl:1
	s_nop 1
	v_add_f32_dpp v224, v224, v224 row_half_mirror row_mask:0xf bank_mask:0xf bound_ctrl:1
	s_nop 1
	v_add_f32_dpp v224, v224, v224 row_mirror row_mask:0xf bank_mask:0xf bound_ctrl:1
	v_mov_b32_e32 v225, v224
	s_nop 1
	v_permlane16_swap_b32_e32 v224, v225
	v_add_f32_e32 v224, v224, v225
	v_mov_b32_e32 v225, v224
	s_nop 1
	v_permlane32_swap_b32_e32 v224, v225
	v_add_f32_e32 v224, v224, v225
	v_fmamk_f32 v224, v224, 0x3a800000, v197
	v_rsq_f32_e32 v226, v224
	s_nop 0
	v_pk_mul_f32 v[232:233], v[232:233], v[226:227] op_sel_hi:[1,0]
	v_pk_mul_f32 v[234:235], v[234:235], v[226:227] op_sel_hi:[1,0]
	v_pk_mul_f32 v[236:237], v[236:237], v[226:227] op_sel_hi:[1,0]
	v_pk_mul_f32 v[238:239], v[238:239], v[226:227] op_sel_hi:[1,0]
	v_pk_mul_f32 v[240:241], v[240:241], v[226:227] op_sel_hi:[1,0]
	v_pk_mul_f32 v[242:243], v[242:243], v[226:227] op_sel_hi:[1,0]
	v_pk_mul_f32 v[244:245], v[244:245], v[226:227] op_sel_hi:[1,0]
	v_pk_mul_f32 v[246:247], v[246:247], v[226:227] op_sel_hi:[1,0]
	v_cvt_pk_bf16_f32 v248, v232, v233
	v_cvt_pk_bf16_f32 v249, v234, v235
	global_store_dwordx2 v[230:231], v[248:249], off offset:0
	v_cvt_pk_bf16_f32 v250, v236, v237
	v_cvt_pk_bf16_f32 v251, v238, v239
	global_store_dwordx2 v[230:231], v[250:251], off offset:512
	v_cvt_pk_bf16_f32 v248, v240, v241
	v_cvt_pk_bf16_f32 v249, v242, v243
	global_store_dwordx2 v[230:231], v[248:249], off offset:1024
	v_cvt_pk_bf16_f32 v250, v244, v245
	v_cvt_pk_bf16_f32 v251, v246, v247
	global_store_dwordx2 v[230:231], v[250:251], off offset:1536
